# v044 minus the 12 redundant s_waitcnt lgkmcnt(0) that follow s_barrier+s_setprio 1 at the head of each GEMM MMA block (lgkmcnt already drained before the barrier)
# speedup vs baseline: 1.0071x; 1.0071x over previous
; #define PG8_STAGE(bufoff, gbase, voff) do { _Pragma("unroll") for (int _i = 0; _i < 2; ++_i) \
;         __builtin_amdgcn_global_load_lds((const unsigned*)((const char*)(gbase) + (voff)[_i]), (PG8_LAS unsigned*)(lds + (bufoff) + ldsw + _i * 8192), 16, 0, 0); } while (0)
; #define PG8_LDA(dst, b, h) do { _Pragma("unroll") for (int m = 0; m < 4; ++m) _Pragma("unroll") for (int k = 0; k < 2; ++k) dst[m][k] = *(const PG8_LAS bf16x8*)(lds + PG8_SA(b, h) + aoff + m * 2048 + k * 1024); } while (0)
; #define PG8_LDB(dst, b, h) do { _Pragma("unroll") for (int n = 0; n < 2; ++n) _Pragma("unroll") for (int k = 0; k < 2; ++k) dst[n][k] = *(const PG8_LAS bf16x8*)(lds + PG8_SB(b, h) + boff + n * 2048 + k * 1024); } while (0)
; #define PG8_MMA(ai, bj, At, Bt) do { __builtin_amdgcn_s_setprio(1); _Pragma("unroll") for (int m = 0; m < 4; ++m) _Pragma("unroll") for (int n = 0; n < 2; ++n) _Pragma("unroll") for (int k = 0; k < 2; ++k) \
;         acc[ai][bj][m][n] = __builtin_amdgcn_mfma_f32_16x16x32_bf16(Bt[n][k], At[m][k], acc[ai][bj][m][n], 0, 0, 0); __builtin_amdgcn_s_setprio(0); } while (0)
; #define PG8_WAIT_V(n) asm volatile("s_waitcnt vmcnt(" #n ")" ::: "memory")
; #define PG8_BAR __builtin_amdgcn_s_barrier()
; template <class Epi, class Sched, bool ALIGN_EPI = false, bool SP2 = false>
; __device__ __forceinline__ void gemm_phase(PG8_LAS unsigned char* lds, const Gemm g, const Sched& S, const Epi& E) {
;     ...
;         for (int t = 0; t < nt; t += 2) {
;             const bool last = (t == nt - 2);
;             const char* a1 = cA + (size_t)(t + 1) * kstep;
;             const char* a2 = last ? nA : cA + (size_t)(t + 2) * kstep; const char* b2 = last ? nB : cB + (size_t)(t + 2) * kstep;
;             const char* a3 = a2 + kstep; const char* b3 = b2 + kstep;
;             if (last && has_next) S.a_ready(nxt);
;             if constexpr (SP2) {
;             PG8_LDB(B0, 0, 0); PG8_LDB(B1, 0, 1); PG8_SCHED; PG8_LDA(At, 0, 0); PG8_STAGE(PG8_SA(1, 1), a1 + hstep, voffA);
;             PG8_WAIT_V(8); PG8_WAIT_L(0); PG8_BAR; PG8_MMA(0, 0, At, B0); PG8_MMA(0, 1, At, B1); PG8_BAR; PG8_SCHED;
;             PG8_LDA(At, 0, 1); PG8_STAGE(PG8_SB(0, 0), b2, voffB); PG8_STAGE(PG8_SB(0, 1), b2 + hstep, voffB); PG8_STAGE(PG8_SA(0, 0), a2, voffA);
;             PG8_WAIT_V(8); PG8_WAIT_L(0); PG8_BAR; PG8_MMA(1, 0, At, B0); PG8_MMA(1, 1, At, B1); PG8_BAR; PG8_SCHED;
.LBB0_117:
	s_add_u32 s50, s48, 0xfff80080
	s_addc_u32 s51, s49, -1
	s_add_i32 s61, 0, 0x10000
	s_cmp_eq_u32 s58, 28
	s_cselect_b32 s77, s1, s51
	s_cselect_b32 s76, s24, s50
	v_add_u32_e32 v0, s61, v234
	s_cselect_b32 s51, s25, s47
	s_cselect_b32 s50, s38, s39
	s_add_i32 s63, 0, 0x14000
	ds_read_b128 v[124:127], v0
	ds_read_b128 v[128:131], v0 offset:1024
	ds_read_b128 v[132:135], v0 offset:2048
	ds_read_b128 v[140:143], v0 offset:3072
	v_add_u32_e32 v0, s63, v234
	ds_read_b128 v[148:151], v0
	ds_read_b128 v[152:155], v0 offset:1024
	ds_read_b128 v[156:159], v0 offset:2048
	ds_read_b128 v[160:163], v0 offset:3072
	v_lshl_add_u64 v[2:3], s[48:49], 0, v[192:193]
	s_add_i32 m0, s82, 0xc000
	ds_read_b128 v[164:167], v235
	ds_read_b128 v[198:201], v235 offset:1024
	ds_read_b128 v[202:205], v235 offset:2048
	ds_read_b128 v[206:209], v235 offset:3072
	ds_read_b128 v[210:213], v235 offset:4096
	ds_read_b128 v[214:217], v235 offset:5120
	ds_read_b128 v[218:221], v235 offset:6144
	ds_read_b128 v[236:239], v235 offset:7168
	global_load_lds_dwordx4 v[2:3], off
	v_lshl_add_u64 v[2:3], s[48:49], 0, v[194:195]
	s_add_i32 m0, s82, 0xe000
	s_nop 0
	global_load_lds_dwordx4 v[2:3], off
	s_waitcnt vmcnt(8)
	s_waitcnt lgkmcnt(0)
	s_barrier
	s_setprio 1
	v_mfma_f32_16x16x32_bf16 v[144:147], v[124:127], v[164:167], v[144:147]
	v_mfma_f32_16x16x32_bf16 v[136:139], v[132:135], v[164:167], v[136:139]
	v_mfma_f32_16x16x32_bf16 v[112:115], v[124:127], v[202:205], v[112:115]
	v_mfma_f32_16x16x32_bf16 v[108:111], v[132:135], v[202:205], v[108:111]
	v_mfma_f32_16x16x32_bf16 v[96:99], v[124:127], v[210:213], v[96:99]
	v_mfma_f32_16x16x32_bf16 v[92:95], v[132:135], v[210:213], v[92:95]
	v_mfma_f32_16x16x32_bf16 v[80:83], v[124:127], v[218:221], v[80:83]
	v_mfma_f32_16x16x32_bf16 v[76:79], v[132:135], v[218:221], v[76:79]
	v_mfma_f32_16x16x32_bf16 v[144:147], v[128:131], v[198:201], v[144:147]
	v_mfma_f32_16x16x32_bf16 v[136:139], v[140:143], v[198:201], v[136:139]
	v_mfma_f32_16x16x32_bf16 v[112:115], v[128:131], v[206:209], v[112:115]
	v_mfma_f32_16x16x32_bf16 v[108:111], v[140:143], v[206:209], v[108:111]
	v_mfma_f32_16x16x32_bf16 v[96:99], v[128:131], v[214:217], v[96:99]
	v_mfma_f32_16x16x32_bf16 v[92:95], v[140:143], v[214:217], v[92:95]
	v_mfma_f32_16x16x32_bf16 v[80:83], v[128:131], v[236:239], v[80:83]
	v_mfma_f32_16x16x32_bf16 v[76:79], v[140:143], v[236:239], v[76:79]
	s_setprio 0
	s_setprio 1
	v_mfma_f32_16x16x32_bf16 v[120:123], v[148:151], v[164:167], v[120:123]
	v_mfma_f32_16x16x32_bf16 v[116:119], v[156:159], v[164:167], v[116:119]
	v_mfma_f32_16x16x32_bf16 v[104:107], v[148:151], v[202:205], v[104:107]
	v_mfma_f32_16x16x32_bf16 v[100:103], v[156:159], v[202:205], v[100:103]
	v_mfma_f32_16x16x32_bf16 v[88:91], v[148:151], v[210:213], v[88:91]
	v_mfma_f32_16x16x32_bf16 v[84:87], v[156:159], v[210:213], v[84:87]
	v_mfma_f32_16x16x32_bf16 v[72:75], v[148:151], v[218:221], v[72:75]
	v_mfma_f32_16x16x32_bf16 v[68:71], v[156:159], v[218:221], v[68:71]
	v_mfma_f32_16x16x32_bf16 v[120:123], v[152:155], v[198:201], v[120:123]
	v_mfma_f32_16x16x32_bf16 v[116:119], v[160:163], v[198:201], v[116:119]
	v_mfma_f32_16x16x32_bf16 v[104:107], v[152:155], v[206:209], v[104:107]
	v_mfma_f32_16x16x32_bf16 v[100:103], v[160:163], v[206:209], v[100:103]
	v_mfma_f32_16x16x32_bf16 v[88:91], v[152:155], v[214:217], v[88:91]
	v_mfma_f32_16x16x32_bf16 v[84:87], v[160:163], v[214:217], v[84:87]
	v_mfma_f32_16x16x32_bf16 v[72:75], v[152:155], v[236:239], v[72:75]
	v_mfma_f32_16x16x32_bf16 v[68:71], v[160:163], v[236:239], v[68:71]
	s_setprio 0
	s_barrier
	s_add_i32 s61, s61, s73
	v_lshl_add_u64 v[168:169], s[50:51], 0, v[182:183]
	s_mov_b32 m0, s61
	ds_read_b128 v[164:167], v235 offset:16384
	ds_read_b128 v[198:201], v235 offset:17408
	ds_read_b128 v[202:205], v235 offset:18432
	ds_read_b128 v[206:209], v235 offset:19456
	ds_read_b128 v[210:213], v235 offset:20480
	ds_read_b128 v[214:217], v235 offset:21504
	ds_read_b128 v[218:221], v235 offset:22528
	ds_read_b128 v[236:239], v235 offset:23552
	global_load_lds_dwordx4 v[168:169], off
	s_add_i32 m0, s61, 0x2000
	s_add_u32 s78, s50, 0x80000
	v_lshl_add_u64 v[222:223], s[50:51], 0, v[186:187]
	s_addc_u32 s79, s51, 0
	s_add_i32 s61, s63, s73
	global_load_lds_dwordx4 v[222:223], off
	v_lshl_add_u64 v[2:3], s[78:79], 0, v[182:183]
	s_mov_b32 m0, s61
	v_lshl_add_u64 v[244:245], s[76:77], 0, v[180:181]
	global_load_lds_dwordx4 v[2:3], off
	v_lshl_add_u64 v[2:3], s[78:79], 0, v[186:187]
	s_add_i32 m0, s61, 0x2000
	v_lshl_add_u64 v[246:247], s[76:77], 0, v[184:185]
	global_load_lds_dwordx4 v[2:3], off
	s_mov_b32 m0, s82
	s_nop 0
	global_load_lds_dwordx4 v[244:245], off
	s_mov_b32 m0, s83
	s_nop 0
	global_load_lds_dwordx4 v[246:247], off
	s_waitcnt vmcnt(8)
	s_waitcnt lgkmcnt(0)
	s_barrier
; #define PG8_STAGE(bufoff, gbase, voff) do { _Pragma("unroll") for (int _i = 0; _i < 2; ++_i) \
;         __builtin_amdgcn_global_load_lds((const unsigned*)((const char*)(gbase) + (voff)[_i]), (PG8_LAS unsigned*)(lds + (bufoff) + ldsw + _i * 8192), 16, 0, 0); } while (0)
; #define PG8_LDA(dst, b, h) do { _Pragma("unroll") for (int m = 0; m < 4; ++m) _Pragma("unroll") for (int k = 0; k < 2; ++k) dst[m][k] = *(const PG8_LAS bf16x8*)(lds + PG8_SA(b, h) + aoff + m * 2048 + k * 1024); } while (0)
; #define PG8_LDB(dst, b, h) do { _Pragma("unroll") for (int n = 0; n < 2; ++n) _Pragma("unroll") for (int k = 0; k < 2; ++k) dst[n][k] = *(const PG8_LAS bf16x8*)(lds + PG8_SB(b, h) + boff + n * 2048 + k * 1024); } while (0)
; #define PG8_MMA(ai, bj, At, Bt) do { __builtin_amdgcn_s_setprio(1); _Pragma("unroll") for (int m = 0; m < 4; ++m) _Pragma("unroll") for (int n = 0; n < 2; ++n) _Pragma("unroll") for (int k = 0; k < 2; ++k) \
;         acc[ai][bj][m][n] = __builtin_amdgcn_mfma_f32_16x16x32_bf16(Bt[n][k], At[m][k], acc[ai][bj][m][n], 0, 0, 0); __builtin_amdgcn_s_setprio(0); } while (0)
; #define PG8_WAIT_V(n) asm volatile("s_waitcnt vmcnt(" #n ")" ::: "memory")
; #define PG8_WAIT_L(n) asm volatile("s_waitcnt lgkmcnt(" #n ")" ::: "memory")
; #define PG8_BAR __builtin_amdgcn_s_barrier()
; #define PG8_SCHED __builtin_amdgcn_sched_barrier(0)
; template <class Epi, class Sched, bool ALIGN_EPI = false, bool SP2 = false>
; __device__ __forceinline__ void gemm_phase(PG8_LAS unsigned char* lds, const Gemm g, const Sched& S, const Epi& E) {
;     ...
;             PG8_WAIT_V(8); PG8_WAIT_L(0); PG8_BAR; PG8_MMA(1, 0, At, B0); PG8_MMA(1, 1, At, B1); PG8_BAR; PG8_SCHED;
;             PG8_LDB(B0, 1, 0); PG8_LDB(B1, 1, 1); PG8_SCHED; PG8_LDA(At, 1, 0); PG8_STAGE(PG8_SA(0, 1), a2 + hstep, voffA);
;             PG8_WAIT_V(8); PG8_WAIT_L(0); PG8_BAR; PG8_MMA(0, 0, At, B0); PG8_MMA(0, 1, At, B1); PG8_BAR; PG8_SCHED;
	s_setprio 1
	v_mfma_f32_16x16x32_bf16 v[64:67], v[124:127], v[164:167], v[64:67]
	v_mfma_f32_16x16x32_bf16 v[60:63], v[132:135], v[164:167], v[60:63]
	v_mfma_f32_16x16x32_bf16 v[48:51], v[124:127], v[202:205], v[48:51]
	v_mfma_f32_16x16x32_bf16 v[44:47], v[132:135], v[202:205], v[44:47]
	v_mfma_f32_16x16x32_bf16 v[32:35], v[124:127], v[210:213], v[32:35]
	v_mfma_f32_16x16x32_bf16 v[28:31], v[132:135], v[210:213], v[28:31]
	v_mfma_f32_16x16x32_bf16 v[16:19], v[124:127], v[218:221], v[16:19]
	v_mfma_f32_16x16x32_bf16 v[12:15], v[132:135], v[218:221], v[12:15]
	v_mfma_f32_16x16x32_bf16 v[64:67], v[128:131], v[198:201], v[64:67]
	v_mfma_f32_16x16x32_bf16 v[60:63], v[140:143], v[198:201], v[60:63]
	v_mfma_f32_16x16x32_bf16 v[48:51], v[128:131], v[206:209], v[48:51]
	v_mfma_f32_16x16x32_bf16 v[44:47], v[140:143], v[206:209], v[44:47]
	v_mfma_f32_16x16x32_bf16 v[32:35], v[128:131], v[214:217], v[32:35]
	v_mfma_f32_16x16x32_bf16 v[28:31], v[140:143], v[214:217], v[28:31]
	v_mfma_f32_16x16x32_bf16 v[16:19], v[128:131], v[236:239], v[16:19]
	v_mfma_f32_16x16x32_bf16 v[12:15], v[140:143], v[236:239], v[12:15]
	s_setprio 0
	s_setprio 1
	v_mfma_f32_16x16x32_bf16 v[56:59], v[148:151], v[164:167], v[56:59]
	v_mfma_f32_16x16x32_bf16 v[52:55], v[156:159], v[164:167], v[52:55]
	v_mfma_f32_16x16x32_bf16 v[40:43], v[148:151], v[202:205], v[40:43]
	v_mfma_f32_16x16x32_bf16 v[36:39], v[156:159], v[202:205], v[36:39]
	v_mfma_f32_16x16x32_bf16 v[24:27], v[148:151], v[210:213], v[24:27]
	v_mfma_f32_16x16x32_bf16 v[20:23], v[156:159], v[210:213], v[20:23]
	v_mfma_f32_16x16x32_bf16 v[8:11], v[148:151], v[218:221], v[8:11]
	v_mfma_f32_16x16x32_bf16 v[2:5], v[156:159], v[218:221], v[4:7]
	v_mfma_f32_16x16x32_bf16 v[56:59], v[152:155], v[198:201], v[56:59]
	v_mfma_f32_16x16x32_bf16 v[52:55], v[160:163], v[198:201], v[52:55]
	v_mfma_f32_16x16x32_bf16 v[40:43], v[152:155], v[206:209], v[40:43]
	v_mfma_f32_16x16x32_bf16 v[36:39], v[160:163], v[206:209], v[36:39]
	v_mfma_f32_16x16x32_bf16 v[24:27], v[152:155], v[214:217], v[24:27]
	v_mfma_f32_16x16x32_bf16 v[20:23], v[160:163], v[214:217], v[20:23]
	v_mfma_f32_16x16x32_bf16 v[8:11], v[152:155], v[236:239], v[8:11]
	v_mfma_f32_16x16x32_bf16 v[2:5], v[160:163], v[236:239], v[2:5]
	s_setprio 0
	s_barrier
	s_add_i32 s61, 0, 0x18000
	v_add_u32_e32 v0, s61, v234
	s_add_i32 s63, 0, 0x1c000
	ds_read_b128 v[124:127], v0
	ds_read_b128 v[128:131], v0 offset:1024
	ds_read_b128 v[132:135], v0 offset:2048
	ds_read_b128 v[140:143], v0 offset:3072
	v_add_u32_e32 v0, s63, v234
	ds_read_b128 v[148:151], v0
	ds_read_b128 v[152:155], v0 offset:1024
	ds_read_b128 v[156:159], v0 offset:2048
	ds_read_b128 v[160:163], v0 offset:3072
	s_add_u32 s76, s76, 0x80000
	s_addc_u32 s77, s77, 0
	s_mov_b32 m0, s84
	v_lshl_add_u64 v[6:7], s[76:77], 0, v[180:181]
	ds_read_b128 v[164:167], v235 offset:32768
	ds_read_b128 v[198:201], v235 offset:33792
	ds_read_b128 v[202:205], v235 offset:34816
	ds_read_b128 v[206:209], v235 offset:35840
	ds_read_b128 v[210:213], v235 offset:36864
	ds_read_b128 v[214:217], v235 offset:37888
	ds_read_b128 v[218:221], v235 offset:38912
	ds_read_b128 v[236:239], v235 offset:39936
	global_load_lds_dwordx4 v[6:7], off
	v_lshl_add_u64 v[6:7], s[76:77], 0, v[184:185]
	s_mov_b32 m0, s85
	s_nop 0
	global_load_lds_dwordx4 v[6:7], off
	s_waitcnt vmcnt(8)
	s_waitcnt lgkmcnt(0)
	s_barrier
	s_setprio 1
	v_mfma_f32_16x16x32_bf16 v[144:147], v[124:127], v[164:167], v[144:147]
	v_mfma_f32_16x16x32_bf16 v[136:139], v[132:135], v[164:167], v[136:139]
	v_mfma_f32_16x16x32_bf16 v[112:115], v[124:127], v[202:205], v[112:115]
	v_mfma_f32_16x16x32_bf16 v[108:111], v[132:135], v[202:205], v[108:111]
	v_mfma_f32_16x16x32_bf16 v[96:99], v[124:127], v[210:213], v[96:99]
	v_mfma_f32_16x16x32_bf16 v[92:95], v[132:135], v[210:213], v[92:95]
	v_mfma_f32_16x16x32_bf16 v[80:83], v[124:127], v[218:221], v[80:83]
	v_mfma_f32_16x16x32_bf16 v[76:79], v[132:135], v[218:221], v[76:79]
	v_mfma_f32_16x16x32_bf16 v[144:147], v[128:131], v[198:201], v[144:147]
	v_mfma_f32_16x16x32_bf16 v[136:139], v[140:143], v[198:201], v[136:139]
	v_mfma_f32_16x16x32_bf16 v[112:115], v[128:131], v[206:209], v[112:115]
	v_mfma_f32_16x16x32_bf16 v[108:111], v[140:143], v[206:209], v[108:111]
	v_mfma_f32_16x16x32_bf16 v[96:99], v[128:131], v[214:217], v[96:99]
	v_mfma_f32_16x16x32_bf16 v[92:95], v[140:143], v[214:217], v[92:95]
	v_mfma_f32_16x16x32_bf16 v[80:83], v[128:131], v[236:239], v[80:83]
	v_mfma_f32_16x16x32_bf16 v[76:79], v[140:143], v[236:239], v[76:79]
	s_setprio 0
	s_setprio 1
	v_mfma_f32_16x16x32_bf16 v[120:123], v[148:151], v[164:167], v[120:123]
	v_mfma_f32_16x16x32_bf16 v[116:119], v[156:159], v[164:167], v[116:119]
	v_mfma_f32_16x16x32_bf16 v[104:107], v[148:151], v[202:205], v[104:107]
	v_mfma_f32_16x16x32_bf16 v[100:103], v[156:159], v[202:205], v[100:103]
	v_mfma_f32_16x16x32_bf16 v[88:91], v[148:151], v[210:213], v[88:91]
	v_mfma_f32_16x16x32_bf16 v[84:87], v[156:159], v[210:213], v[84:87]
	v_mfma_f32_16x16x32_bf16 v[72:75], v[148:151], v[218:221], v[72:75]
	v_mfma_f32_16x16x32_bf16 v[68:71], v[156:159], v[218:221], v[68:71]
	v_mfma_f32_16x16x32_bf16 v[120:123], v[152:155], v[198:201], v[120:123]
	v_mfma_f32_16x16x32_bf16 v[116:119], v[160:163], v[198:201], v[116:119]
	v_mfma_f32_16x16x32_bf16 v[104:107], v[152:155], v[206:209], v[104:107]
	v_mfma_f32_16x16x32_bf16 v[100:103], v[160:163], v[206:209], v[100:103]
	v_mfma_f32_16x16x32_bf16 v[88:91], v[152:155], v[214:217], v[88:91]
	v_mfma_f32_16x16x32_bf16 v[84:87], v[160:163], v[214:217], v[84:87]
	v_mfma_f32_16x16x32_bf16 v[72:75], v[152:155], v[236:239], v[72:75]
	v_mfma_f32_16x16x32_bf16 v[68:71], v[160:163], v[236:239], v[68:71]
	s_setprio 0
	s_barrier
; #define PG8_STAGE(bufoff, gbase, voff) do { _Pragma("unroll") for (int _i = 0; _i < 2; ++_i) \
;         __builtin_amdgcn_global_load_lds((const unsigned*)((const char*)(gbase) + (voff)[_i]), (PG8_LAS unsigned*)(lds + (bufoff) + ldsw + _i * 8192), 16, 0, 0); } while (0)
; #define PG8_LDA(dst, b, h) do { _Pragma("unroll") for (int m = 0; m < 4; ++m) _Pragma("unroll") for (int k = 0; k < 2; ++k) dst[m][k] = *(const PG8_LAS bf16x8*)(lds + PG8_SA(b, h) + aoff + m * 2048 + k * 1024); } while (0)
; #define PG8_MMA(ai, bj, At, Bt) do { __builtin_amdgcn_s_setprio(1); _Pragma("unroll") for (int m = 0; m < 4; ++m) _Pragma("unroll") for (int n = 0; n < 2; ++n) _Pragma("unroll") for (int k = 0; k < 2; ++k) \
;         acc[ai][bj][m][n] = __builtin_amdgcn_mfma_f32_16x16x32_bf16(Bt[n][k], At[m][k], acc[ai][bj][m][n], 0, 0, 0); __builtin_amdgcn_s_setprio(0); } while (0)
; #define PG8_WAIT_V(n) asm volatile("s_waitcnt vmcnt(" #n ")" ::: "memory")
; #define PG8_WAIT_L(n) asm volatile("s_waitcnt lgkmcnt(" #n ")" ::: "memory")
; #define PG8_BAR __builtin_amdgcn_s_barrier()
; #define PG8_SCHED __builtin_amdgcn_sched_barrier(0)
; template <class Epi, class Sched, bool ALIGN_EPI = false, bool SP2 = false>
; __device__ __forceinline__ void gemm_phase(PG8_LAS unsigned char* lds, const Gemm g, const Sched& S, const Epi& E) {
;     ...
;             PG8_LDA(At, 1, 1); PG8_STAGE(PG8_SB(1, 0), b3, voffB); PG8_STAGE(PG8_SB(1, 1), b3 + hstep, voffB); PG8_STAGE(PG8_SA(1, 0), a3, voffA);
;             PG8_WAIT_V(8); PG8_WAIT_L(0); PG8_BAR; PG8_MMA(1, 0, At, B0); PG8_MMA(1, 1, At, B1); PG8_BAR; PG8_SCHED;
;     ...
;         if constexpr (ALIGN_EPI) { if (wr == 0) PG8_BAR; }
	s_add_i32 s61, s61, s73
	v_lshl_add_u64 v[6:7], v[168:169], 0, s[12:13]
	s_mov_b32 m0, s61
	ds_read_b128 v[164:167], v235 offset:49152
	ds_read_b128 v[198:201], v235 offset:50176
	ds_read_b128 v[202:205], v235 offset:51200
	ds_read_b128 v[206:209], v235 offset:52224
	ds_read_b128 v[210:213], v235 offset:53248
	ds_read_b128 v[214:217], v235 offset:54272
	ds_read_b128 v[218:221], v235 offset:55296
	ds_read_b128 v[236:239], v235 offset:56320
	global_load_lds_dwordx4 v[6:7], off
	s_add_i32 m0, s61, 0x2000
	s_add_u32 s50, s50, 0x80080
	v_lshl_add_u64 v[6:7], v[222:223], 0, s[12:13]
	s_addc_u32 s51, s51, 0
	s_add_i32 s61, s63, s73
	global_load_lds_dwordx4 v[6:7], off
	v_lshl_add_u64 v[6:7], s[50:51], 0, v[182:183]
	s_mov_b32 m0, s61
	s_nop 0
	global_load_lds_dwordx4 v[6:7], off
	v_lshl_add_u64 v[6:7], s[50:51], 0, v[186:187]
	s_add_i32 m0, s61, 0x2000
	s_nop 0
	global_load_lds_dwordx4 v[6:7], off
	v_lshl_add_u64 v[6:7], v[244:245], 0, s[12:13]
	s_mov_b32 m0, s87
	s_nop 0
	global_load_lds_dwordx4 v[6:7], off
	v_lshl_add_u64 v[6:7], v[246:247], 0, s[12:13]
	s_mov_b32 m0, s88
	s_nop 0
	global_load_lds_dwordx4 v[6:7], off
	s_waitcnt vmcnt(8)
	s_waitcnt lgkmcnt(0)
	s_barrier
	s_setprio 1
	v_mfma_f32_16x16x32_bf16 v[64:67], v[124:127], v[164:167], v[64:67]
	v_mfma_f32_16x16x32_bf16 v[60:63], v[132:135], v[164:167], v[60:63]
	v_mfma_f32_16x16x32_bf16 v[48:51], v[124:127], v[202:205], v[48:51]
	v_mfma_f32_16x16x32_bf16 v[44:47], v[132:135], v[202:205], v[44:47]
	v_mfma_f32_16x16x32_bf16 v[32:35], v[124:127], v[210:213], v[32:35]
	v_mfma_f32_16x16x32_bf16 v[28:31], v[132:135], v[210:213], v[28:31]
	v_mfma_f32_16x16x32_bf16 v[16:19], v[124:127], v[218:221], v[16:19]
	v_mfma_f32_16x16x32_bf16 v[12:15], v[132:135], v[218:221], v[12:15]
	v_mfma_f32_16x16x32_bf16 v[64:67], v[128:131], v[198:201], v[64:67]
	v_mfma_f32_16x16x32_bf16 v[60:63], v[140:143], v[198:201], v[60:63]
	v_mfma_f32_16x16x32_bf16 v[48:51], v[128:131], v[206:209], v[48:51]
	v_mfma_f32_16x16x32_bf16 v[44:47], v[140:143], v[206:209], v[44:47]
	v_mfma_f32_16x16x32_bf16 v[32:35], v[128:131], v[214:217], v[32:35]
	v_mfma_f32_16x16x32_bf16 v[28:31], v[140:143], v[214:217], v[28:31]
	v_mfma_f32_16x16x32_bf16 v[16:19], v[128:131], v[236:239], v[16:19]
	v_mfma_f32_16x16x32_bf16 v[12:15], v[140:143], v[236:239], v[12:15]
	s_setprio 0
	s_setprio 1
	v_mfma_f32_16x16x32_bf16 v[56:59], v[148:151], v[164:167], v[56:59]
	v_mfma_f32_16x16x32_bf16 v[52:55], v[156:159], v[164:167], v[52:55]
	v_mfma_f32_16x16x32_bf16 v[40:43], v[148:151], v[202:205], v[40:43]
	v_mfma_f32_16x16x32_bf16 v[36:39], v[156:159], v[202:205], v[36:39]
	v_mfma_f32_16x16x32_bf16 v[24:27], v[148:151], v[210:213], v[24:27]
	v_mfma_f32_16x16x32_bf16 v[20:23], v[156:159], v[210:213], v[20:23]
	v_mfma_f32_16x16x32_bf16 v[6:9], v[148:151], v[218:221], v[8:11]
	v_mfma_f32_16x16x32_bf16 v[2:5], v[156:159], v[218:221], v[2:5]
	v_mfma_f32_16x16x32_bf16 v[56:59], v[152:155], v[198:201], v[56:59]
	v_mfma_f32_16x16x32_bf16 v[52:55], v[160:163], v[198:201], v[52:55]
	v_mfma_f32_16x16x32_bf16 v[40:43], v[152:155], v[206:209], v[40:43]
	v_mfma_f32_16x16x32_bf16 v[36:39], v[160:163], v[206:209], v[36:39]
	v_mfma_f32_16x16x32_bf16 v[24:27], v[152:155], v[214:217], v[24:27]
	v_mfma_f32_16x16x32_bf16 v[20:23], v[160:163], v[214:217], v[20:23]
	v_mfma_f32_16x16x32_bf16 v[8:11], v[152:155], v[236:239], v[6:9]
	v_mfma_f32_16x16x32_bf16 v[4:7], v[160:163], v[236:239], v[2:5]
	s_setprio 0
	s_barrier
	s_add_i32 s58, s58, 2
	s_add_u32 s48, s48, 0x100
	s_addc_u32 s49, s49, 0
	s_add_u32 s39, s39, 0x100
	s_addc_u32 s47, s47, 0
	s_cmp_gt_u32 s58, 29
	s_cbranch_scc0 .LBB0_117
	s_and_b64 vcc, exec, s[30:31]
	s_cbranch_vccz .LBB0_120
	s_barrier

; #define PG8_STAGE(bufoff, gbase, voff) do { _Pragma("unroll") for (int _i = 0; _i < 2; ++_i) \
;         __builtin_amdgcn_global_load_lds((const unsigned*)((const char*)(gbase) + (voff)[_i]), (PG8_LAS unsigned*)(lds + (bufoff) + ldsw + _i * 8192), 16, 0, 0); } while (0)
; #define PG8_LDA(dst, b, h) do { _Pragma("unroll") for (int m = 0; m < 4; ++m) _Pragma("unroll") for (int k = 0; k < 2; ++k) dst[m][k] = *(const PG8_LAS bf16x8*)(lds + PG8_SA(b, h) + aoff + m * 2048 + k * 1024); } while (0)
; #define PG8_LDB(dst, b, h) do { _Pragma("unroll") for (int n = 0; n < 2; ++n) _Pragma("unroll") for (int k = 0; k < 2; ++k) dst[n][k] = *(const PG8_LAS bf16x8*)(lds + PG8_SB(b, h) + boff + n * 2048 + k * 1024); } while (0)
; #define PG8_MMA(ai, bj, At, Bt) do { __builtin_amdgcn_s_setprio(1); _Pragma("unroll") for (int m = 0; m < 4; ++m) _Pragma("unroll") for (int n = 0; n < 2; ++n) _Pragma("unroll") for (int k = 0; k < 2; ++k) \
;         acc[ai][bj][m][n] = __builtin_amdgcn_mfma_f32_16x16x32_bf16(Bt[n][k], At[m][k], acc[ai][bj][m][n], 0, 0, 0); __builtin_amdgcn_s_setprio(0); } while (0)
; #define PG8_WAIT_V(n) asm volatile("s_waitcnt vmcnt(" #n ")" ::: "memory")
; #define PG8_BAR __builtin_amdgcn_s_barrier()
; template <class Epi, class Sched, bool ALIGN_EPI = false, bool SP2 = false>
; __device__ __forceinline__ void gemm_phase(PG8_LAS unsigned char* lds, const Gemm g, const Sched& S, const Epi& E) {
;     ...
;         for (int t = 0; t < nt; t += 2) {
;             const bool last = (t == nt - 2);
;             const char* a1 = cA + (size_t)(t + 1) * kstep;
;             const char* a2 = last ? nA : cA + (size_t)(t + 2) * kstep; const char* b2 = last ? nB : cB + (size_t)(t + 2) * kstep;
;             const char* a3 = a2 + kstep; const char* b3 = b2 + kstep;
;             if (last && has_next) S.a_ready(nxt);
;             if constexpr (SP2) {
;             PG8_LDB(B0, 0, 0); PG8_LDB(B1, 0, 1); PG8_SCHED; PG8_LDA(At, 0, 0); PG8_STAGE(PG8_SA(1, 1), a1 + hstep, voffA);
;             PG8_WAIT_V(8); PG8_WAIT_L(0); PG8_BAR; PG8_MMA(0, 0, At, B0); PG8_MMA(0, 1, At, B1); PG8_BAR; PG8_SCHED;
;             PG8_LDA(At, 0, 1); PG8_STAGE(PG8_SB(0, 0), b2, voffB); PG8_STAGE(PG8_SB(0, 1), b2 + hstep, voffB); PG8_STAGE(PG8_SA(0, 0), a2, voffA);
;             PG8_WAIT_V(8); PG8_WAIT_L(0); PG8_BAR; PG8_MMA(1, 0, At, B0); PG8_MMA(1, 1, At, B1); PG8_BAR; PG8_SCHED;
.LBB0_1427:
	s_add_i32 s96, s74, 2
	s_add_u32 s97, s44, 0x80
	s_addc_u32 s75, s45, 0
	s_add_i32 s27, 0, 0x10000
	s_cmp_eq_u32 s91, s74
	s_cselect_b32 s75, s24, s75
	s_cselect_b32 s74, s25, s97
	s_cselect_b32 vcc_hi, s53, s95
	s_cselect_b32 vcc_lo, s61, s94
	s_add_i32 s97, 0, 0x14000
	v_add_u32_e32 v142, s27, v185
	v_add_u32_e32 v168, s97, v185
	ds_read_b128 v[130:133], v142
	ds_read_b128 v[134:137], v142 offset:1024
	ds_read_b128 v[138:141], v142 offset:2048
	ds_read_b128 v[142:145], v142 offset:3072
	ds_read_b128 v[146:149], v168
	ds_read_b128 v[150:153], v168 offset:1024
	ds_read_b128 v[164:167], v168 offset:2048
	ds_read_b128 v[180:183], v168 offset:3072
	v_lshl_add_u64 v[168:169], s[44:45], 0, v[160:161]
	s_add_i32 m0, s83, 0xc000
	ds_read_b128 v[190:193], v187
	ds_read_b128 v[194:197], v187 offset:1024
	ds_read_b128 v[198:201], v187 offset:2048
	ds_read_b128 v[202:205], v187 offset:3072
	ds_read_b128 v[206:209], v187 offset:4096
	ds_read_b128 v[210:213], v187 offset:5120
	ds_read_b128 v[214:217], v187 offset:6144
	ds_read_b128 v[218:221], v187 offset:7168
	global_load_lds_dwordx4 v[168:169], off
	v_lshl_add_u64 v[168:169], s[44:45], 0, v[162:163]
	s_add_i32 m0, s83, 0xe000
	s_nop 0
	global_load_lds_dwordx4 v[168:169], off
	s_waitcnt vmcnt(8)
	s_waitcnt lgkmcnt(0)
	s_barrier
	s_setprio 1
	v_mfma_f32_16x16x32_bf16 v[126:129], v[130:133], v[190:193], v[126:129]
	v_mfma_f32_16x16x32_bf16 v[122:125], v[138:141], v[190:193], v[122:125]
	v_mfma_f32_16x16x32_bf16 v[110:113], v[130:133], v[198:201], v[110:113]
	v_mfma_f32_16x16x32_bf16 v[106:109], v[138:141], v[198:201], v[106:109]
	v_mfma_f32_16x16x32_bf16 v[94:97], v[130:133], v[206:209], v[94:97]
	v_mfma_f32_16x16x32_bf16 v[90:93], v[138:141], v[206:209], v[90:93]
	v_mfma_f32_16x16x32_bf16 v[78:81], v[130:133], v[214:217], v[78:81]
	v_mfma_f32_16x16x32_bf16 v[74:77], v[138:141], v[214:217], v[74:77]
	v_mfma_f32_16x16x32_bf16 v[126:129], v[134:137], v[194:197], v[126:129]
	v_mfma_f32_16x16x32_bf16 v[122:125], v[142:145], v[194:197], v[122:125]
	v_mfma_f32_16x16x32_bf16 v[110:113], v[134:137], v[202:205], v[110:113]
	v_mfma_f32_16x16x32_bf16 v[106:109], v[142:145], v[202:205], v[106:109]
	v_mfma_f32_16x16x32_bf16 v[94:97], v[134:137], v[210:213], v[94:97]
	v_mfma_f32_16x16x32_bf16 v[90:93], v[142:145], v[210:213], v[90:93]
	v_mfma_f32_16x16x32_bf16 v[78:81], v[134:137], v[218:221], v[78:81]
	v_mfma_f32_16x16x32_bf16 v[74:77], v[142:145], v[218:221], v[74:77]
	s_setprio 0
	s_setprio 1
	v_mfma_f32_16x16x32_bf16 v[118:121], v[146:149], v[190:193], v[118:121]
	v_mfma_f32_16x16x32_bf16 v[114:117], v[164:167], v[190:193], v[114:117]
	v_mfma_f32_16x16x32_bf16 v[102:105], v[146:149], v[198:201], v[102:105]
	v_mfma_f32_16x16x32_bf16 v[98:101], v[164:167], v[198:201], v[98:101]
	v_mfma_f32_16x16x32_bf16 v[86:89], v[146:149], v[206:209], v[86:89]
	v_mfma_f32_16x16x32_bf16 v[82:85], v[164:167], v[206:209], v[82:85]
	v_mfma_f32_16x16x32_bf16 v[70:73], v[146:149], v[214:217], v[70:73]
	v_mfma_f32_16x16x32_bf16 v[66:69], v[164:167], v[214:217], v[66:69]
	v_mfma_f32_16x16x32_bf16 v[118:121], v[150:153], v[194:197], v[118:121]
	v_mfma_f32_16x16x32_bf16 v[114:117], v[180:183], v[194:197], v[114:117]
	v_mfma_f32_16x16x32_bf16 v[102:105], v[150:153], v[202:205], v[102:105]
	v_mfma_f32_16x16x32_bf16 v[98:101], v[180:183], v[202:205], v[98:101]
	v_mfma_f32_16x16x32_bf16 v[86:89], v[150:153], v[210:213], v[86:89]
	v_mfma_f32_16x16x32_bf16 v[82:85], v[180:183], v[210:213], v[82:85]
	v_mfma_f32_16x16x32_bf16 v[70:73], v[150:153], v[218:221], v[70:73]
	v_mfma_f32_16x16x32_bf16 v[66:69], v[180:183], v[218:221], v[66:69]
	s_setprio 0
	s_barrier
	s_add_i32 s27, s27, s82
	v_lshl_add_u64 v[168:169], vcc, 0, v[0:1]
	s_mov_b32 m0, s27
	ds_read_b128 v[190:193], v187 offset:16384
	ds_read_b128 v[194:197], v187 offset:17408
	ds_read_b128 v[198:201], v187 offset:18432
	ds_read_b128 v[202:205], v187 offset:19456
	ds_read_b128 v[206:209], v187 offset:20480
	ds_read_b128 v[210:213], v187 offset:21504
	ds_read_b128 v[214:217], v187 offset:22528
	ds_read_b128 v[218:221], v187 offset:23552
	global_load_lds_dwordx4 v[168:169], off
	s_add_i32 m0, s27, 0x2000
	v_lshl_add_u64 v[222:223], vcc, 0, v[154:155]
	s_add_u32 vcc_lo, vcc_lo, s70
	s_addc_u32 vcc_hi, vcc_hi, 0
	s_add_i32 s27, s97, s82
	global_load_lds_dwordx4 v[222:223], off
	v_lshl_add_u64 v[232:233], vcc, 0, v[0:1]
	s_mov_b32 m0, s27
	v_lshl_add_u64 v[234:235], vcc, 0, v[154:155]
	global_load_lds_dwordx4 v[232:233], off
	s_add_i32 m0, s27, 0x2000
	v_lshl_add_u64 v[236:237], s[74:75], 0, v[158:159]
	global_load_lds_dwordx4 v[234:235], off
	s_mov_b32 m0, s83
	v_lshl_add_u64 v[238:239], s[74:75], 0, v[156:157]
	global_load_lds_dwordx4 v[236:237], off
	s_mov_b32 m0, s84
	s_nop 0
	global_load_lds_dwordx4 v[238:239], off
	s_waitcnt vmcnt(8)
	s_waitcnt lgkmcnt(0)
	s_barrier
; #define PG8_STAGE(bufoff, gbase, voff) do { _Pragma("unroll") for (int _i = 0; _i < 2; ++_i) \
;         __builtin_amdgcn_global_load_lds((const unsigned*)((const char*)(gbase) + (voff)[_i]), (PG8_LAS unsigned*)(lds + (bufoff) + ldsw + _i * 8192), 16, 0, 0); } while (0)
; #define PG8_LDA(dst, b, h) do { _Pragma("unroll") for (int m = 0; m < 4; ++m) _Pragma("unroll") for (int k = 0; k < 2; ++k) dst[m][k] = *(const PG8_LAS bf16x8*)(lds + PG8_SA(b, h) + aoff + m * 2048 + k * 1024); } while (0)
; #define PG8_LDB(dst, b, h) do { _Pragma("unroll") for (int n = 0; n < 2; ++n) _Pragma("unroll") for (int k = 0; k < 2; ++k) dst[n][k] = *(const PG8_LAS bf16x8*)(lds + PG8_SB(b, h) + boff + n * 2048 + k * 1024); } while (0)
; #define PG8_MMA(ai, bj, At, Bt) do { __builtin_amdgcn_s_setprio(1); _Pragma("unroll") for (int m = 0; m < 4; ++m) _Pragma("unroll") for (int n = 0; n < 2; ++n) _Pragma("unroll") for (int k = 0; k < 2; ++k) \
;         acc[ai][bj][m][n] = __builtin_amdgcn_mfma_f32_16x16x32_bf16(Bt[n][k], At[m][k], acc[ai][bj][m][n], 0, 0, 0); __builtin_amdgcn_s_setprio(0); } while (0)
; #define PG8_WAIT_V(n) asm volatile("s_waitcnt vmcnt(" #n ")" ::: "memory")
; #define PG8_WAIT_L(n) asm volatile("s_waitcnt lgkmcnt(" #n ")" ::: "memory")
; #define PG8_BAR __builtin_amdgcn_s_barrier()
; #define PG8_SCHED __builtin_amdgcn_sched_barrier(0)
; template <class Epi, class Sched, bool ALIGN_EPI = false, bool SP2 = false>
; __device__ __forceinline__ void gemm_phase(PG8_LAS unsigned char* lds, const Gemm g, const Sched& S, const Epi& E) {
;     ...
;             PG8_WAIT_V(8); PG8_WAIT_L(0); PG8_BAR; PG8_MMA(1, 0, At, B0); PG8_MMA(1, 1, At, B1); PG8_BAR; PG8_SCHED;
;             PG8_LDB(B0, 1, 0); PG8_LDB(B1, 1, 1); PG8_SCHED; PG8_LDA(At, 1, 0); PG8_STAGE(PG8_SA(0, 1), a2 + hstep, voffA);
;             PG8_WAIT_V(8); PG8_WAIT_L(0); PG8_BAR; PG8_MMA(0, 0, At, B0); PG8_MMA(0, 1, At, B1); PG8_BAR; PG8_SCHED;
	s_setprio 1
	v_mfma_f32_16x16x32_bf16 v[62:65], v[130:133], v[190:193], v[62:65]
	v_mfma_f32_16x16x32_bf16 v[58:61], v[138:141], v[190:193], v[58:61]
	v_mfma_f32_16x16x32_bf16 v[46:49], v[130:133], v[198:201], v[46:49]
	v_mfma_f32_16x16x32_bf16 v[42:45], v[138:141], v[198:201], v[42:45]
	v_mfma_f32_16x16x32_bf16 v[30:33], v[130:133], v[206:209], v[30:33]
	v_mfma_f32_16x16x32_bf16 v[26:29], v[138:141], v[206:209], v[26:29]
	v_mfma_f32_16x16x32_bf16 v[14:17], v[130:133], v[214:217], v[14:17]
	v_mfma_f32_16x16x32_bf16 v[10:13], v[138:141], v[214:217], v[10:13]
	v_mfma_f32_16x16x32_bf16 v[62:65], v[134:137], v[194:197], v[62:65]
	v_mfma_f32_16x16x32_bf16 v[58:61], v[142:145], v[194:197], v[58:61]
	v_mfma_f32_16x16x32_bf16 v[46:49], v[134:137], v[202:205], v[46:49]
	v_mfma_f32_16x16x32_bf16 v[42:45], v[142:145], v[202:205], v[42:45]
	v_mfma_f32_16x16x32_bf16 v[30:33], v[134:137], v[210:213], v[30:33]
	v_mfma_f32_16x16x32_bf16 v[26:29], v[142:145], v[210:213], v[26:29]
	v_mfma_f32_16x16x32_bf16 v[14:17], v[134:137], v[218:221], v[14:17]
	v_mfma_f32_16x16x32_bf16 v[10:13], v[142:145], v[218:221], v[10:13]
	s_setprio 0
	s_setprio 1
	v_mfma_f32_16x16x32_bf16 v[54:57], v[146:149], v[190:193], v[54:57]
	v_mfma_f32_16x16x32_bf16 v[50:53], v[164:167], v[190:193], v[50:53]
	v_mfma_f32_16x16x32_bf16 v[38:41], v[146:149], v[198:201], v[38:41]
	v_mfma_f32_16x16x32_bf16 v[34:37], v[164:167], v[198:201], v[34:37]
	v_mfma_f32_16x16x32_bf16 v[22:25], v[146:149], v[206:209], v[22:25]
	v_mfma_f32_16x16x32_bf16 v[18:21], v[164:167], v[206:209], v[18:21]
	v_mfma_f32_16x16x32_bf16 v[6:9], v[146:149], v[214:217], v[6:9]
	v_mfma_f32_16x16x32_bf16 v[2:5], v[164:167], v[214:217], v[2:5]
	v_mfma_f32_16x16x32_bf16 v[54:57], v[150:153], v[194:197], v[54:57]
	v_mfma_f32_16x16x32_bf16 v[50:53], v[180:183], v[194:197], v[50:53]
	v_mfma_f32_16x16x32_bf16 v[38:41], v[150:153], v[202:205], v[38:41]
	v_mfma_f32_16x16x32_bf16 v[34:37], v[180:183], v[202:205], v[34:37]
	v_mfma_f32_16x16x32_bf16 v[22:25], v[150:153], v[210:213], v[22:25]
	v_mfma_f32_16x16x32_bf16 v[18:21], v[180:183], v[210:213], v[18:21]
	v_mfma_f32_16x16x32_bf16 v[6:9], v[150:153], v[218:221], v[6:9]
	v_mfma_f32_16x16x32_bf16 v[2:5], v[180:183], v[218:221], v[2:5]
	s_setprio 0
	s_barrier
	s_add_i32 s27, 0, 0x18000
	s_add_i32 s97, 0, 0x1c000
	v_add_u32_e32 v142, s27, v185
	v_add_u32_e32 v180, s97, v185
	ds_read_b128 v[130:133], v142
	ds_read_b128 v[134:137], v142 offset:1024
	ds_read_b128 v[138:141], v142 offset:2048
	ds_read_b128 v[142:145], v142 offset:3072
	ds_read_b128 v[146:149], v180
	ds_read_b128 v[150:153], v180 offset:1024
	ds_read_b128 v[164:167], v180 offset:2048
	ds_read_b128 v[180:183], v180 offset:3072
	s_add_u32 s74, s74, s70
	s_addc_u32 s75, s75, 0
	s_mov_b32 m0, s85
	v_lshl_add_u64 v[244:245], s[74:75], 0, v[158:159]
	ds_read_b128 v[190:193], v187 offset:32768
	ds_read_b128 v[194:197], v187 offset:33792
	ds_read_b128 v[198:201], v187 offset:34816
	ds_read_b128 v[202:205], v187 offset:35840
	ds_read_b128 v[206:209], v187 offset:36864
	ds_read_b128 v[210:213], v187 offset:37888
	ds_read_b128 v[214:217], v187 offset:38912
	ds_read_b128 v[218:221], v187 offset:39936
	global_load_lds_dwordx4 v[244:245], off
	v_lshl_add_u64 v[244:245], s[74:75], 0, v[156:157]
	s_mov_b32 m0, s86
	s_nop 0
	global_load_lds_dwordx4 v[244:245], off
	s_waitcnt vmcnt(8)
	s_waitcnt lgkmcnt(0)
	s_barrier
	s_setprio 1
	v_mfma_f32_16x16x32_bf16 v[126:129], v[130:133], v[190:193], v[126:129]
	v_mfma_f32_16x16x32_bf16 v[122:125], v[138:141], v[190:193], v[122:125]
	v_mfma_f32_16x16x32_bf16 v[110:113], v[130:133], v[198:201], v[110:113]
	v_mfma_f32_16x16x32_bf16 v[106:109], v[138:141], v[198:201], v[106:109]
	v_mfma_f32_16x16x32_bf16 v[94:97], v[130:133], v[206:209], v[94:97]
	v_mfma_f32_16x16x32_bf16 v[90:93], v[138:141], v[206:209], v[90:93]
	v_mfma_f32_16x16x32_bf16 v[78:81], v[130:133], v[214:217], v[78:81]
	v_mfma_f32_16x16x32_bf16 v[74:77], v[138:141], v[214:217], v[74:77]
	v_mfma_f32_16x16x32_bf16 v[126:129], v[134:137], v[194:197], v[126:129]
	v_mfma_f32_16x16x32_bf16 v[122:125], v[142:145], v[194:197], v[122:125]
	v_mfma_f32_16x16x32_bf16 v[110:113], v[134:137], v[202:205], v[110:113]
	v_mfma_f32_16x16x32_bf16 v[106:109], v[142:145], v[202:205], v[106:109]
	v_mfma_f32_16x16x32_bf16 v[94:97], v[134:137], v[210:213], v[94:97]
	v_mfma_f32_16x16x32_bf16 v[90:93], v[142:145], v[210:213], v[90:93]
	v_mfma_f32_16x16x32_bf16 v[78:81], v[134:137], v[218:221], v[78:81]
	v_mfma_f32_16x16x32_bf16 v[74:77], v[142:145], v[218:221], v[74:77]
	s_setprio 0
	s_setprio 1
	v_mfma_f32_16x16x32_bf16 v[118:121], v[146:149], v[190:193], v[118:121]
	v_mfma_f32_16x16x32_bf16 v[114:117], v[164:167], v[190:193], v[114:117]
	v_mfma_f32_16x16x32_bf16 v[102:105], v[146:149], v[198:201], v[102:105]
	v_mfma_f32_16x16x32_bf16 v[98:101], v[164:167], v[198:201], v[98:101]
	v_mfma_f32_16x16x32_bf16 v[86:89], v[146:149], v[206:209], v[86:89]
	v_mfma_f32_16x16x32_bf16 v[82:85], v[164:167], v[206:209], v[82:85]
	v_mfma_f32_16x16x32_bf16 v[70:73], v[146:149], v[214:217], v[70:73]
	v_mfma_f32_16x16x32_bf16 v[66:69], v[164:167], v[214:217], v[66:69]
	v_mfma_f32_16x16x32_bf16 v[118:121], v[150:153], v[194:197], v[118:121]
	v_mfma_f32_16x16x32_bf16 v[114:117], v[180:183], v[194:197], v[114:117]
	v_mfma_f32_16x16x32_bf16 v[102:105], v[150:153], v[202:205], v[102:105]
	v_mfma_f32_16x16x32_bf16 v[98:101], v[180:183], v[202:205], v[98:101]
	v_mfma_f32_16x16x32_bf16 v[86:89], v[150:153], v[210:213], v[86:89]
	v_mfma_f32_16x16x32_bf16 v[82:85], v[180:183], v[210:213], v[82:85]
	v_mfma_f32_16x16x32_bf16 v[70:73], v[150:153], v[218:221], v[70:73]
	v_mfma_f32_16x16x32_bf16 v[66:69], v[180:183], v[218:221], v[66:69]
	s_setprio 0
	s_barrier
; #define PG8_STAGE(bufoff, gbase, voff) do { _Pragma("unroll") for (int _i = 0; _i < 2; ++_i) \
;         __builtin_amdgcn_global_load_lds((const unsigned*)((const char*)(gbase) + (voff)[_i]), (PG8_LAS unsigned*)(lds + (bufoff) + ldsw + _i * 8192), 16, 0, 0); } while (0)
; #define PG8_LDA(dst, b, h) do { _Pragma("unroll") for (int m = 0; m < 4; ++m) _Pragma("unroll") for (int k = 0; k < 2; ++k) dst[m][k] = *(const PG8_LAS bf16x8*)(lds + PG8_SA(b, h) + aoff + m * 2048 + k * 1024); } while (0)
; #define PG8_MMA(ai, bj, At, Bt) do { __builtin_amdgcn_s_setprio(1); _Pragma("unroll") for (int m = 0; m < 4; ++m) _Pragma("unroll") for (int n = 0; n < 2; ++n) _Pragma("unroll") for (int k = 0; k < 2; ++k) \
;         acc[ai][bj][m][n] = __builtin_amdgcn_mfma_f32_16x16x32_bf16(Bt[n][k], At[m][k], acc[ai][bj][m][n], 0, 0, 0); __builtin_amdgcn_s_setprio(0); } while (0)
; #define PG8_WAIT_V(n) asm volatile("s_waitcnt vmcnt(" #n ")" ::: "memory")
; #define PG8_WAIT_L(n) asm volatile("s_waitcnt lgkmcnt(" #n ")" ::: "memory")
; #define PG8_BAR __builtin_amdgcn_s_barrier()
; #define PG8_SCHED __builtin_amdgcn_sched_barrier(0)
; template <class Epi, class Sched, bool ALIGN_EPI = false, bool SP2 = false>
; __device__ __forceinline__ void gemm_phase(PG8_LAS unsigned char* lds, const Gemm g, const Sched& S, const Epi& E) {
;     ...
;             PG8_LDA(At, 1, 1); PG8_STAGE(PG8_SB(1, 0), b3, voffB); PG8_STAGE(PG8_SB(1, 1), b3 + hstep, voffB); PG8_STAGE(PG8_SA(1, 0), a3, voffA);
;             PG8_WAIT_V(8); PG8_WAIT_L(0); PG8_BAR; PG8_MMA(1, 0, At, B0); PG8_MMA(1, 1, At, B1); PG8_BAR; PG8_SCHED;
;     ...
;         if constexpr (ALIGN_EPI) { if (wr == 0) PG8_BAR; }
	s_add_i32 s27, s27, s82
	v_lshl_add_u64 v[168:169], v[168:169], 0, s[12:13]
	s_mov_b32 m0, s27
	ds_read_b128 v[190:193], v187 offset:49152
	ds_read_b128 v[194:197], v187 offset:50176
	ds_read_b128 v[198:201], v187 offset:51200
	ds_read_b128 v[202:205], v187 offset:52224
	ds_read_b128 v[206:209], v187 offset:53248
	ds_read_b128 v[210:213], v187 offset:54272
	ds_read_b128 v[214:217], v187 offset:55296
	ds_read_b128 v[218:221], v187 offset:56320
	global_load_lds_dwordx4 v[168:169], off
	v_lshl_add_u64 v[168:169], v[222:223], 0, s[12:13]
	s_add_i32 m0, s27, 0x2000
	s_add_i32 s27, s97, s82
	global_load_lds_dwordx4 v[168:169], off
	v_lshl_add_u64 v[168:169], v[232:233], 0, s[12:13]
	s_mov_b32 m0, s27
	s_nop 0
	global_load_lds_dwordx4 v[168:169], off
	v_lshl_add_u64 v[168:169], v[234:235], 0, s[12:13]
	s_add_i32 m0, s27, 0x2000
	s_nop 0
	global_load_lds_dwordx4 v[168:169], off
	v_lshl_add_u64 v[168:169], v[236:237], 0, s[12:13]
	s_mov_b32 m0, s89
	s_nop 0
	global_load_lds_dwordx4 v[168:169], off
	v_lshl_add_u64 v[168:169], v[238:239], 0, s[12:13]
	s_mov_b32 m0, s90
	s_nop 0
	global_load_lds_dwordx4 v[168:169], off
	s_waitcnt vmcnt(8)
	s_waitcnt lgkmcnt(0)
	s_barrier
	s_setprio 1
	v_mfma_f32_16x16x32_bf16 v[62:65], v[130:133], v[190:193], v[62:65]
	v_mfma_f32_16x16x32_bf16 v[58:61], v[138:141], v[190:193], v[58:61]
	v_mfma_f32_16x16x32_bf16 v[46:49], v[130:133], v[198:201], v[46:49]
	v_mfma_f32_16x16x32_bf16 v[42:45], v[138:141], v[198:201], v[42:45]
	v_mfma_f32_16x16x32_bf16 v[30:33], v[130:133], v[206:209], v[30:33]
	v_mfma_f32_16x16x32_bf16 v[26:29], v[138:141], v[206:209], v[26:29]
	v_mfma_f32_16x16x32_bf16 v[14:17], v[130:133], v[214:217], v[14:17]
	v_mfma_f32_16x16x32_bf16 v[10:13], v[138:141], v[214:217], v[10:13]
	v_mfma_f32_16x16x32_bf16 v[62:65], v[134:137], v[194:197], v[62:65]
	v_mfma_f32_16x16x32_bf16 v[58:61], v[142:145], v[194:197], v[58:61]
	v_mfma_f32_16x16x32_bf16 v[46:49], v[134:137], v[202:205], v[46:49]
	v_mfma_f32_16x16x32_bf16 v[42:45], v[142:145], v[202:205], v[42:45]
	v_mfma_f32_16x16x32_bf16 v[30:33], v[134:137], v[210:213], v[30:33]
	v_mfma_f32_16x16x32_bf16 v[26:29], v[142:145], v[210:213], v[26:29]
	v_mfma_f32_16x16x32_bf16 v[14:17], v[134:137], v[218:221], v[14:17]
	v_mfma_f32_16x16x32_bf16 v[10:13], v[142:145], v[218:221], v[10:13]
	s_setprio 0
	s_setprio 1
	v_mfma_f32_16x16x32_bf16 v[54:57], v[146:149], v[190:193], v[54:57]
	v_mfma_f32_16x16x32_bf16 v[50:53], v[164:167], v[190:193], v[50:53]
	v_mfma_f32_16x16x32_bf16 v[38:41], v[146:149], v[198:201], v[38:41]
	v_mfma_f32_16x16x32_bf16 v[34:37], v[164:167], v[198:201], v[34:37]
	v_mfma_f32_16x16x32_bf16 v[22:25], v[146:149], v[206:209], v[22:25]
	v_mfma_f32_16x16x32_bf16 v[18:21], v[164:167], v[206:209], v[18:21]
	v_mfma_f32_16x16x32_bf16 v[6:9], v[146:149], v[214:217], v[6:9]
	v_mfma_f32_16x16x32_bf16 v[2:5], v[164:167], v[214:217], v[2:5]
	v_mfma_f32_16x16x32_bf16 v[54:57], v[150:153], v[194:197], v[54:57]
	v_mfma_f32_16x16x32_bf16 v[50:53], v[180:183], v[194:197], v[50:53]
	v_mfma_f32_16x16x32_bf16 v[38:41], v[150:153], v[202:205], v[38:41]
	v_mfma_f32_16x16x32_bf16 v[34:37], v[180:183], v[202:205], v[34:37]
	v_mfma_f32_16x16x32_bf16 v[22:25], v[150:153], v[210:213], v[22:25]
	v_mfma_f32_16x16x32_bf16 v[18:21], v[180:183], v[210:213], v[18:21]
	v_mfma_f32_16x16x32_bf16 v[6:9], v[150:153], v[218:221], v[6:9]
	v_mfma_f32_16x16x32_bf16 v[2:5], v[180:183], v[218:221], v[2:5]
	s_setprio 0
	s_barrier
	s_add_u32 s44, s44, 0x100
	s_addc_u32 s45, s45, 0
	s_add_u32 s94, s94, 0x100
	s_addc_u32 s95, s95, 0
	s_cmp_ge_u32 s96, s88
	s_mov_b32 s74, s96
	s_cbranch_scc0 .LBB0_1427
	s_and_b64 vcc, exec, s[48:49]
	s_cbranch_vccz .LBB0_1430
	s_barrier

; #define PG8_STAGE(bufoff, gbase, voff) do { _Pragma("unroll") for (int _i = 0; _i < 2; ++_i) \
;         __builtin_amdgcn_global_load_lds((const unsigned*)((const char*)(gbase) + (voff)[_i]), (PG8_LAS unsigned*)(lds + (bufoff) + ldsw + _i * 8192), 16, 0, 0); } while (0)
; #define PG8_LDA(dst, b, h) do { _Pragma("unroll") for (int m = 0; m < 4; ++m) _Pragma("unroll") for (int k = 0; k < 2; ++k) dst[m][k] = *(const PG8_LAS bf16x8*)(lds + PG8_SA(b, h) + aoff + m * 2048 + k * 1024); } while (0)
; #define PG8_LDB(dst, b, h) do { _Pragma("unroll") for (int n = 0; n < 2; ++n) _Pragma("unroll") for (int k = 0; k < 2; ++k) dst[n][k] = *(const PG8_LAS bf16x8*)(lds + PG8_SB(b, h) + boff + n * 2048 + k * 1024); } while (0)
; #define PG8_MMA(ai, bj, At, Bt) do { __builtin_amdgcn_s_setprio(1); _Pragma("unroll") for (int m = 0; m < 4; ++m) _Pragma("unroll") for (int n = 0; n < 2; ++n) _Pragma("unroll") for (int k = 0; k < 2; ++k) \
;         acc[ai][bj][m][n] = __builtin_amdgcn_mfma_f32_16x16x32_bf16(Bt[n][k], At[m][k], acc[ai][bj][m][n], 0, 0, 0); __builtin_amdgcn_s_setprio(0); } while (0)
; #define PG8_WAIT_V(n) asm volatile("s_waitcnt vmcnt(" #n ")" ::: "memory")
; #define PG8_BAR __builtin_amdgcn_s_barrier()
; template <class Epi, class Sched, bool ALIGN_EPI = false, bool SP2 = false>
; __device__ __forceinline__ void gemm_phase(PG8_LAS unsigned char* lds, const Gemm g, const Sched& S, const Epi& E) {
;     ...
;         for (int t = 0; t < nt; t += 2) {
;             const bool last = (t == nt - 2);
;             const char* a1 = cA + (size_t)(t + 1) * kstep;
;             const char* a2 = last ? nA : cA + (size_t)(t + 2) * kstep; const char* b2 = last ? nB : cB + (size_t)(t + 2) * kstep;
;             const char* a3 = a2 + kstep; const char* b3 = b2 + kstep;
;             if (last && has_next) S.a_ready(nxt);
;             if constexpr (SP2) {
;             PG8_LDB(B0, 0, 0); PG8_LDB(B1, 0, 1); PG8_SCHED; PG8_LDA(At, 0, 0); PG8_STAGE(PG8_SA(1, 1), a1 + hstep, voffA);
;             PG8_WAIT_V(8); PG8_WAIT_L(0); PG8_BAR; PG8_MMA(0, 0, At, B0); PG8_MMA(0, 1, At, B1); PG8_BAR; PG8_SCHED;
;             PG8_LDA(At, 0, 1); PG8_STAGE(PG8_SB(0, 0), b2, voffB); PG8_STAGE(PG8_SB(0, 1), b2 + hstep, voffB); PG8_STAGE(PG8_SA(0, 0), a2, voffA);
;             PG8_WAIT_V(8); PG8_WAIT_L(0); PG8_BAR; PG8_MMA(1, 0, At, B0); PG8_MMA(1, 1, At, B1); PG8_BAR; PG8_SCHED;
.LBB0_1497:
	s_add_u32 s50, s0, 0xfff80080
	s_addc_u32 s51, s1, -1
	s_add_i32 s81, 0, 0x10000
	s_cmp_eq_u32 s80, 28
	s_cselect_b32 s53, s24, s51
	s_cselect_b32 s52, s25, s50
	s_cselect_b32 s51, s43, s75
	s_cselect_b32 s50, s45, s74
	s_add_i32 s84, 0, 0x14000
	v_add_u32_e32 v152, s81, v160
	v_add_u32_e32 v156, s84, v160
	ds_read_b128 v[140:143], v152
	ds_read_b128 v[144:147], v152 offset:1024
	ds_read_b128 v[148:151], v152 offset:2048
	ds_read_b128 v[152:155], v152 offset:3072
	ds_read_b128 v[164:167], v156
	ds_read_b128 v[180:183], v156 offset:1024
	ds_read_b128 v[184:187], v156 offset:2048
	ds_read_b128 v[190:193], v156 offset:3072
	v_lshl_add_u64 v[156:157], s[0:1], 0, v[136:137]
	s_add_i32 m0, s39, 0xc000
	ds_read_b128 v[194:197], v162
	ds_read_b128 v[198:201], v162 offset:1024
	ds_read_b128 v[202:205], v162 offset:2048
	ds_read_b128 v[206:209], v162 offset:3072
	ds_read_b128 v[210:213], v162 offset:4096
	ds_read_b128 v[214:217], v162 offset:5120
	ds_read_b128 v[218:221], v162 offset:6144
	ds_read_b128 v[232:235], v162 offset:7168
	global_load_lds_dwordx4 v[156:157], off
	v_lshl_add_u64 v[156:157], s[0:1], 0, v[138:139]
	s_add_i32 m0, s39, 0xe000
	s_nop 0
	global_load_lds_dwordx4 v[156:157], off
	s_waitcnt vmcnt(8)
	s_waitcnt lgkmcnt(0)
	s_barrier
	s_setprio 1
	v_mfma_f32_16x16x32_bf16 v[126:129], v[140:143], v[194:197], v[126:129]
	v_mfma_f32_16x16x32_bf16 v[122:125], v[148:151], v[194:197], v[122:125]
	v_mfma_f32_16x16x32_bf16 v[110:113], v[140:143], v[202:205], v[110:113]
	v_mfma_f32_16x16x32_bf16 v[106:109], v[148:151], v[202:205], v[106:109]
	v_mfma_f32_16x16x32_bf16 v[94:97], v[140:143], v[210:213], v[94:97]
	v_mfma_f32_16x16x32_bf16 v[90:93], v[148:151], v[210:213], v[90:93]
	v_mfma_f32_16x16x32_bf16 v[78:81], v[140:143], v[218:221], v[78:81]
	v_mfma_f32_16x16x32_bf16 v[74:77], v[148:151], v[218:221], v[74:77]
	v_mfma_f32_16x16x32_bf16 v[126:129], v[144:147], v[198:201], v[126:129]
	v_mfma_f32_16x16x32_bf16 v[122:125], v[152:155], v[198:201], v[122:125]
	v_mfma_f32_16x16x32_bf16 v[110:113], v[144:147], v[206:209], v[110:113]
	v_mfma_f32_16x16x32_bf16 v[106:109], v[152:155], v[206:209], v[106:109]
	v_mfma_f32_16x16x32_bf16 v[94:97], v[144:147], v[214:217], v[94:97]
	v_mfma_f32_16x16x32_bf16 v[90:93], v[152:155], v[214:217], v[90:93]
	v_mfma_f32_16x16x32_bf16 v[78:81], v[144:147], v[232:235], v[78:81]
	v_mfma_f32_16x16x32_bf16 v[74:77], v[152:155], v[232:235], v[74:77]
	s_setprio 0
	s_setprio 1
	v_mfma_f32_16x16x32_bf16 v[118:121], v[164:167], v[194:197], v[118:121]
	v_mfma_f32_16x16x32_bf16 v[114:117], v[184:187], v[194:197], v[114:117]
	v_mfma_f32_16x16x32_bf16 v[102:105], v[164:167], v[202:205], v[102:105]
	v_mfma_f32_16x16x32_bf16 v[98:101], v[184:187], v[202:205], v[98:101]
	v_mfma_f32_16x16x32_bf16 v[86:89], v[164:167], v[210:213], v[86:89]
	v_mfma_f32_16x16x32_bf16 v[82:85], v[184:187], v[210:213], v[82:85]
	v_mfma_f32_16x16x32_bf16 v[70:73], v[164:167], v[218:221], v[70:73]
	v_mfma_f32_16x16x32_bf16 v[66:69], v[184:187], v[218:221], v[66:69]
	v_mfma_f32_16x16x32_bf16 v[118:121], v[180:183], v[198:201], v[118:121]
	v_mfma_f32_16x16x32_bf16 v[114:117], v[190:193], v[198:201], v[114:117]
	v_mfma_f32_16x16x32_bf16 v[102:105], v[180:183], v[206:209], v[102:105]
	v_mfma_f32_16x16x32_bf16 v[98:101], v[190:193], v[206:209], v[98:101]
	v_mfma_f32_16x16x32_bf16 v[86:89], v[180:183], v[214:217], v[86:89]
	v_mfma_f32_16x16x32_bf16 v[82:85], v[190:193], v[214:217], v[82:85]
	v_mfma_f32_16x16x32_bf16 v[70:73], v[180:183], v[232:235], v[70:73]
	v_mfma_f32_16x16x32_bf16 v[66:69], v[190:193], v[232:235], v[66:69]
	s_setprio 0
	s_barrier
	s_add_i32 s81, s81, s38
	v_lshl_add_u64 v[156:157], s[50:51], 0, v[0:1]
	s_mov_b32 m0, s81
	ds_read_b128 v[194:197], v162 offset:16384
	ds_read_b128 v[198:201], v162 offset:17408
	ds_read_b128 v[202:205], v162 offset:18432
	ds_read_b128 v[206:209], v162 offset:19456
	ds_read_b128 v[210:213], v162 offset:20480
	ds_read_b128 v[214:217], v162 offset:21504
	ds_read_b128 v[218:221], v162 offset:22528
	ds_read_b128 v[232:235], v162 offset:23552
	global_load_lds_dwordx4 v[156:157], off
	s_add_i32 m0, s81, 0x2000
	s_add_u32 s82, s50, 0x80000
	v_lshl_add_u64 v[168:169], s[50:51], 0, v[130:131]
	s_addc_u32 s83, s51, 0
	s_add_i32 s81, s84, s38
	global_load_lds_dwordx4 v[168:169], off
	v_lshl_add_u64 v[222:223], s[82:83], 0, v[0:1]
	s_mov_b32 m0, s81
	v_lshl_add_u64 v[236:237], s[52:53], 0, v[132:133]
	global_load_lds_dwordx4 v[222:223], off
	v_lshl_add_u64 v[222:223], s[82:83], 0, v[130:131]
	s_add_i32 m0, s81, 0x2000
	s_nop 0
	global_load_lds_dwordx4 v[222:223], off
	v_lshl_add_u64 v[222:223], s[52:53], 0, v[134:135]
	s_mov_b32 m0, s39
	s_nop 0
	global_load_lds_dwordx4 v[222:223], off
	s_mov_b32 m0, s58
	s_nop 0
	global_load_lds_dwordx4 v[236:237], off
	s_waitcnt vmcnt(8)
	s_waitcnt lgkmcnt(0)
	s_barrier
; #define PG8_STAGE(bufoff, gbase, voff) do { _Pragma("unroll") for (int _i = 0; _i < 2; ++_i) \
;         __builtin_amdgcn_global_load_lds((const unsigned*)((const char*)(gbase) + (voff)[_i]), (PG8_LAS unsigned*)(lds + (bufoff) + ldsw + _i * 8192), 16, 0, 0); } while (0)
; #define PG8_LDA(dst, b, h) do { _Pragma("unroll") for (int m = 0; m < 4; ++m) _Pragma("unroll") for (int k = 0; k < 2; ++k) dst[m][k] = *(const PG8_LAS bf16x8*)(lds + PG8_SA(b, h) + aoff + m * 2048 + k * 1024); } while (0)
; #define PG8_LDB(dst, b, h) do { _Pragma("unroll") for (int n = 0; n < 2; ++n) _Pragma("unroll") for (int k = 0; k < 2; ++k) dst[n][k] = *(const PG8_LAS bf16x8*)(lds + PG8_SB(b, h) + boff + n * 2048 + k * 1024); } while (0)
; #define PG8_MMA(ai, bj, At, Bt) do { __builtin_amdgcn_s_setprio(1); _Pragma("unroll") for (int m = 0; m < 4; ++m) _Pragma("unroll") for (int n = 0; n < 2; ++n) _Pragma("unroll") for (int k = 0; k < 2; ++k) \
;         acc[ai][bj][m][n] = __builtin_amdgcn_mfma_f32_16x16x32_bf16(Bt[n][k], At[m][k], acc[ai][bj][m][n], 0, 0, 0); __builtin_amdgcn_s_setprio(0); } while (0)
; #define PG8_WAIT_V(n) asm volatile("s_waitcnt vmcnt(" #n ")" ::: "memory")
; #define PG8_WAIT_L(n) asm volatile("s_waitcnt lgkmcnt(" #n ")" ::: "memory")
; #define PG8_BAR __builtin_amdgcn_s_barrier()
; #define PG8_SCHED __builtin_amdgcn_sched_barrier(0)
; template <class Epi, class Sched, bool ALIGN_EPI = false, bool SP2 = false>
; __device__ __forceinline__ void gemm_phase(PG8_LAS unsigned char* lds, const Gemm g, const Sched& S, const Epi& E) {
;     ...
;             PG8_WAIT_V(8); PG8_WAIT_L(0); PG8_BAR; PG8_MMA(1, 0, At, B0); PG8_MMA(1, 1, At, B1); PG8_BAR; PG8_SCHED;
;             PG8_LDB(B0, 1, 0); PG8_LDB(B1, 1, 1); PG8_SCHED; PG8_LDA(At, 1, 0); PG8_STAGE(PG8_SA(0, 1), a2 + hstep, voffA);
;             PG8_WAIT_V(8); PG8_WAIT_L(0); PG8_BAR; PG8_MMA(0, 0, At, B0); PG8_MMA(0, 1, At, B1); PG8_BAR; PG8_SCHED;
	s_setprio 1
	v_mfma_f32_16x16x32_bf16 v[62:65], v[140:143], v[194:197], v[62:65]
	v_mfma_f32_16x16x32_bf16 v[58:61], v[148:151], v[194:197], v[58:61]
	v_mfma_f32_16x16x32_bf16 v[46:49], v[140:143], v[202:205], v[46:49]
	v_mfma_f32_16x16x32_bf16 v[42:45], v[148:151], v[202:205], v[42:45]
	v_mfma_f32_16x16x32_bf16 v[30:33], v[140:143], v[210:213], v[30:33]
	v_mfma_f32_16x16x32_bf16 v[26:29], v[148:151], v[210:213], v[26:29]
	v_mfma_f32_16x16x32_bf16 v[14:17], v[140:143], v[218:221], v[14:17]
	v_mfma_f32_16x16x32_bf16 v[10:13], v[148:151], v[218:221], v[10:13]
	v_mfma_f32_16x16x32_bf16 v[62:65], v[144:147], v[198:201], v[62:65]
	v_mfma_f32_16x16x32_bf16 v[58:61], v[152:155], v[198:201], v[58:61]
	v_mfma_f32_16x16x32_bf16 v[46:49], v[144:147], v[206:209], v[46:49]
	v_mfma_f32_16x16x32_bf16 v[42:45], v[152:155], v[206:209], v[42:45]
	v_mfma_f32_16x16x32_bf16 v[30:33], v[144:147], v[214:217], v[30:33]
	v_mfma_f32_16x16x32_bf16 v[26:29], v[152:155], v[214:217], v[26:29]
	v_mfma_f32_16x16x32_bf16 v[14:17], v[144:147], v[232:235], v[14:17]
	v_mfma_f32_16x16x32_bf16 v[10:13], v[152:155], v[232:235], v[10:13]
	s_setprio 0
	s_setprio 1
	v_mfma_f32_16x16x32_bf16 v[54:57], v[164:167], v[194:197], v[54:57]
	v_mfma_f32_16x16x32_bf16 v[50:53], v[184:187], v[194:197], v[50:53]
	v_mfma_f32_16x16x32_bf16 v[38:41], v[164:167], v[202:205], v[38:41]
	v_mfma_f32_16x16x32_bf16 v[34:37], v[184:187], v[202:205], v[34:37]
	v_mfma_f32_16x16x32_bf16 v[22:25], v[164:167], v[210:213], v[22:25]
	v_mfma_f32_16x16x32_bf16 v[18:21], v[184:187], v[210:213], v[18:21]
	v_mfma_f32_16x16x32_bf16 v[6:9], v[164:167], v[218:221], v[6:9]
	v_mfma_f32_16x16x32_bf16 v[2:5], v[184:187], v[218:221], v[2:5]
	v_mfma_f32_16x16x32_bf16 v[54:57], v[180:183], v[198:201], v[54:57]
	v_mfma_f32_16x16x32_bf16 v[50:53], v[190:193], v[198:201], v[50:53]
	v_mfma_f32_16x16x32_bf16 v[38:41], v[180:183], v[206:209], v[38:41]
	v_mfma_f32_16x16x32_bf16 v[34:37], v[190:193], v[206:209], v[34:37]
	v_mfma_f32_16x16x32_bf16 v[22:25], v[180:183], v[214:217], v[22:25]
	v_mfma_f32_16x16x32_bf16 v[18:21], v[190:193], v[214:217], v[18:21]
	v_mfma_f32_16x16x32_bf16 v[6:9], v[180:183], v[232:235], v[6:9]
	v_mfma_f32_16x16x32_bf16 v[2:5], v[190:193], v[232:235], v[2:5]
	s_setprio 0
	s_barrier
	s_add_i32 s81, 0, 0x18000
	s_add_i32 s82, 0, 0x1c000
	v_add_u32_e32 v152, s81, v160
	v_add_u32_e32 v158, s82, v160
	ds_read_b128 v[140:143], v152
	ds_read_b128 v[144:147], v152 offset:1024
	ds_read_b128 v[148:151], v152 offset:2048
	ds_read_b128 v[152:155], v152 offset:3072
	ds_read_b128 v[164:167], v158
	ds_read_b128 v[180:183], v158 offset:1024
	ds_read_b128 v[184:187], v158 offset:2048
	ds_read_b128 v[190:193], v158 offset:3072
	s_add_u32 s52, s52, 0x80000
	s_addc_u32 s53, s53, 0
	s_mov_b32 m0, s60
	v_lshl_add_u64 v[238:239], s[52:53], 0, v[134:135]
	ds_read_b128 v[194:197], v162 offset:32768
	ds_read_b128 v[198:201], v162 offset:33792
	ds_read_b128 v[202:205], v162 offset:34816
	ds_read_b128 v[206:209], v162 offset:35840
	ds_read_b128 v[210:213], v162 offset:36864
	ds_read_b128 v[214:217], v162 offset:37888
	ds_read_b128 v[218:221], v162 offset:38912
	ds_read_b128 v[232:235], v162 offset:39936
	global_load_lds_dwordx4 v[238:239], off
	v_lshl_add_u64 v[238:239], s[52:53], 0, v[132:133]
	s_mov_b32 m0, s61
	s_nop 0
	global_load_lds_dwordx4 v[238:239], off
	s_waitcnt vmcnt(8)
	s_waitcnt lgkmcnt(0)
	s_barrier
	s_setprio 1
	v_mfma_f32_16x16x32_bf16 v[126:129], v[140:143], v[194:197], v[126:129]
	v_mfma_f32_16x16x32_bf16 v[122:125], v[148:151], v[194:197], v[122:125]
	v_mfma_f32_16x16x32_bf16 v[110:113], v[140:143], v[202:205], v[110:113]
	v_mfma_f32_16x16x32_bf16 v[106:109], v[148:151], v[202:205], v[106:109]
	v_mfma_f32_16x16x32_bf16 v[94:97], v[140:143], v[210:213], v[94:97]
	v_mfma_f32_16x16x32_bf16 v[90:93], v[148:151], v[210:213], v[90:93]
	v_mfma_f32_16x16x32_bf16 v[78:81], v[140:143], v[218:221], v[78:81]
	v_mfma_f32_16x16x32_bf16 v[74:77], v[148:151], v[218:221], v[74:77]
	v_mfma_f32_16x16x32_bf16 v[126:129], v[144:147], v[198:201], v[126:129]
	v_mfma_f32_16x16x32_bf16 v[122:125], v[152:155], v[198:201], v[122:125]
	v_mfma_f32_16x16x32_bf16 v[110:113], v[144:147], v[206:209], v[110:113]
	v_mfma_f32_16x16x32_bf16 v[106:109], v[152:155], v[206:209], v[106:109]
	v_mfma_f32_16x16x32_bf16 v[94:97], v[144:147], v[214:217], v[94:97]
	v_mfma_f32_16x16x32_bf16 v[90:93], v[152:155], v[214:217], v[90:93]
	v_mfma_f32_16x16x32_bf16 v[78:81], v[144:147], v[232:235], v[78:81]
	v_mfma_f32_16x16x32_bf16 v[74:77], v[152:155], v[232:235], v[74:77]
	s_setprio 0
	s_setprio 1
	v_mfma_f32_16x16x32_bf16 v[118:121], v[164:167], v[194:197], v[118:121]
	v_mfma_f32_16x16x32_bf16 v[114:117], v[184:187], v[194:197], v[114:117]
	v_mfma_f32_16x16x32_bf16 v[102:105], v[164:167], v[202:205], v[102:105]
	v_mfma_f32_16x16x32_bf16 v[98:101], v[184:187], v[202:205], v[98:101]
	v_mfma_f32_16x16x32_bf16 v[86:89], v[164:167], v[210:213], v[86:89]
	v_mfma_f32_16x16x32_bf16 v[82:85], v[184:187], v[210:213], v[82:85]
	v_mfma_f32_16x16x32_bf16 v[70:73], v[164:167], v[218:221], v[70:73]
	v_mfma_f32_16x16x32_bf16 v[66:69], v[184:187], v[218:221], v[66:69]
	v_mfma_f32_16x16x32_bf16 v[118:121], v[180:183], v[198:201], v[118:121]
	v_mfma_f32_16x16x32_bf16 v[114:117], v[190:193], v[198:201], v[114:117]
	v_mfma_f32_16x16x32_bf16 v[102:105], v[180:183], v[206:209], v[102:105]
	v_mfma_f32_16x16x32_bf16 v[98:101], v[190:193], v[206:209], v[98:101]
	v_mfma_f32_16x16x32_bf16 v[86:89], v[180:183], v[214:217], v[86:89]
	v_mfma_f32_16x16x32_bf16 v[82:85], v[190:193], v[214:217], v[82:85]
	v_mfma_f32_16x16x32_bf16 v[70:73], v[180:183], v[232:235], v[70:73]
	v_mfma_f32_16x16x32_bf16 v[66:69], v[190:193], v[232:235], v[66:69]
	s_setprio 0
	s_barrier
; #define PG8_STAGE(bufoff, gbase, voff) do { _Pragma("unroll") for (int _i = 0; _i < 2; ++_i) \
;         __builtin_amdgcn_global_load_lds((const unsigned*)((const char*)(gbase) + (voff)[_i]), (PG8_LAS unsigned*)(lds + (bufoff) + ldsw + _i * 8192), 16, 0, 0); } while (0)
; #define PG8_LDA(dst, b, h) do { _Pragma("unroll") for (int m = 0; m < 4; ++m) _Pragma("unroll") for (int k = 0; k < 2; ++k) dst[m][k] = *(const PG8_LAS bf16x8*)(lds + PG8_SA(b, h) + aoff + m * 2048 + k * 1024); } while (0)
; #define PG8_MMA(ai, bj, At, Bt) do { __builtin_amdgcn_s_setprio(1); _Pragma("unroll") for (int m = 0; m < 4; ++m) _Pragma("unroll") for (int n = 0; n < 2; ++n) _Pragma("unroll") for (int k = 0; k < 2; ++k) \
;         acc[ai][bj][m][n] = __builtin_amdgcn_mfma_f32_16x16x32_bf16(Bt[n][k], At[m][k], acc[ai][bj][m][n], 0, 0, 0); __builtin_amdgcn_s_setprio(0); } while (0)
; #define PG8_WAIT_V(n) asm volatile("s_waitcnt vmcnt(" #n ")" ::: "memory")
; #define PG8_WAIT_L(n) asm volatile("s_waitcnt lgkmcnt(" #n ")" ::: "memory")
; #define PG8_BAR __builtin_amdgcn_s_barrier()
; #define PG8_SCHED __builtin_amdgcn_sched_barrier(0)
; template <class Epi, class Sched, bool ALIGN_EPI = false, bool SP2 = false>
; __device__ __forceinline__ void gemm_phase(PG8_LAS unsigned char* lds, const Gemm g, const Sched& S, const Epi& E) {
;     ...
;             PG8_LDA(At, 1, 1); PG8_STAGE(PG8_SB(1, 0), b3, voffB); PG8_STAGE(PG8_SB(1, 1), b3 + hstep, voffB); PG8_STAGE(PG8_SA(1, 0), a3, voffA);
;             PG8_WAIT_V(8); PG8_WAIT_L(0); PG8_BAR; PG8_MMA(1, 0, At, B0); PG8_MMA(1, 1, At, B1); PG8_BAR; PG8_SCHED;
;     ...
;         if constexpr (ALIGN_EPI) { if (wr == 0) PG8_BAR; }
	s_add_i32 s52, s81, s38
	v_lshl_add_u64 v[156:157], v[156:157], 0, s[12:13]
	s_mov_b32 m0, s52
	ds_read_b128 v[194:197], v162 offset:49152
	ds_read_b128 v[198:201], v162 offset:50176
	ds_read_b128 v[202:205], v162 offset:51200
	ds_read_b128 v[206:209], v162 offset:52224
	ds_read_b128 v[210:213], v162 offset:53248
	ds_read_b128 v[214:217], v162 offset:54272
	ds_read_b128 v[218:221], v162 offset:55296
	ds_read_b128 v[232:235], v162 offset:56320
	global_load_lds_dwordx4 v[156:157], off
	s_add_i32 m0, s52, 0x2000
	s_add_u32 s50, s50, 0x80080
	v_lshl_add_u64 v[156:157], v[168:169], 0, s[12:13]
	s_addc_u32 s51, s51, 0
	s_add_i32 s52, s82, s38
	global_load_lds_dwordx4 v[156:157], off
	v_lshl_add_u64 v[156:157], s[50:51], 0, v[0:1]
	s_mov_b32 m0, s52
	s_nop 0
	global_load_lds_dwordx4 v[156:157], off
	v_lshl_add_u64 v[156:157], s[50:51], 0, v[130:131]
	s_add_i32 m0, s52, 0x2000
	s_nop 0
	global_load_lds_dwordx4 v[156:157], off
	v_lshl_add_u64 v[156:157], v[222:223], 0, s[12:13]
	s_mov_b32 m0, s62
	s_nop 0
	global_load_lds_dwordx4 v[156:157], off
	v_lshl_add_u64 v[156:157], v[236:237], 0, s[12:13]
	s_mov_b32 m0, s63
	s_nop 0
	global_load_lds_dwordx4 v[156:157], off
	s_waitcnt vmcnt(8)
	s_waitcnt lgkmcnt(0)
	s_barrier
	s_setprio 1
	v_mfma_f32_16x16x32_bf16 v[62:65], v[140:143], v[194:197], v[62:65]
	v_mfma_f32_16x16x32_bf16 v[58:61], v[148:151], v[194:197], v[58:61]
	v_mfma_f32_16x16x32_bf16 v[46:49], v[140:143], v[202:205], v[46:49]
	v_mfma_f32_16x16x32_bf16 v[42:45], v[148:151], v[202:205], v[42:45]
	v_mfma_f32_16x16x32_bf16 v[30:33], v[140:143], v[210:213], v[30:33]
	v_mfma_f32_16x16x32_bf16 v[26:29], v[148:151], v[210:213], v[26:29]
	v_mfma_f32_16x16x32_bf16 v[14:17], v[140:143], v[218:221], v[14:17]
	v_mfma_f32_16x16x32_bf16 v[10:13], v[148:151], v[218:221], v[10:13]
	v_mfma_f32_16x16x32_bf16 v[62:65], v[144:147], v[198:201], v[62:65]
	v_mfma_f32_16x16x32_bf16 v[58:61], v[152:155], v[198:201], v[58:61]
	v_mfma_f32_16x16x32_bf16 v[46:49], v[144:147], v[206:209], v[46:49]
	v_mfma_f32_16x16x32_bf16 v[42:45], v[152:155], v[206:209], v[42:45]
	v_mfma_f32_16x16x32_bf16 v[30:33], v[144:147], v[214:217], v[30:33]
	v_mfma_f32_16x16x32_bf16 v[26:29], v[152:155], v[214:217], v[26:29]
	v_mfma_f32_16x16x32_bf16 v[14:17], v[144:147], v[232:235], v[14:17]
	v_mfma_f32_16x16x32_bf16 v[10:13], v[152:155], v[232:235], v[10:13]
	s_setprio 0
	s_setprio 1
	v_mfma_f32_16x16x32_bf16 v[54:57], v[164:167], v[194:197], v[54:57]
	v_mfma_f32_16x16x32_bf16 v[50:53], v[184:187], v[194:197], v[50:53]
	v_mfma_f32_16x16x32_bf16 v[38:41], v[164:167], v[202:205], v[38:41]
	v_mfma_f32_16x16x32_bf16 v[34:37], v[184:187], v[202:205], v[34:37]
	v_mfma_f32_16x16x32_bf16 v[22:25], v[164:167], v[210:213], v[22:25]
	v_mfma_f32_16x16x32_bf16 v[18:21], v[184:187], v[210:213], v[18:21]
	v_mfma_f32_16x16x32_bf16 v[6:9], v[164:167], v[218:221], v[6:9]
	v_mfma_f32_16x16x32_bf16 v[2:5], v[184:187], v[218:221], v[2:5]
	v_mfma_f32_16x16x32_bf16 v[54:57], v[180:183], v[198:201], v[54:57]
	v_mfma_f32_16x16x32_bf16 v[50:53], v[190:193], v[198:201], v[50:53]
	v_mfma_f32_16x16x32_bf16 v[38:41], v[180:183], v[206:209], v[38:41]
	v_mfma_f32_16x16x32_bf16 v[34:37], v[190:193], v[206:209], v[34:37]
	v_mfma_f32_16x16x32_bf16 v[22:25], v[180:183], v[214:217], v[22:25]
	v_mfma_f32_16x16x32_bf16 v[18:21], v[190:193], v[214:217], v[18:21]
	v_mfma_f32_16x16x32_bf16 v[6:9], v[180:183], v[232:235], v[6:9]
	v_mfma_f32_16x16x32_bf16 v[2:5], v[190:193], v[232:235], v[2:5]
	s_setprio 0
	s_barrier
	s_add_i32 s80, s80, 2
	s_add_u32 s0, s0, 0x100
	s_addc_u32 s1, s1, 0
	s_add_u32 s74, s74, 0x100
	s_addc_u32 s75, s75, 0
	s_cmp_gt_u32 s80, 29
	s_cbranch_scc0 .LBB0_1497
	s_and_b64 vcc, exec, s[30:31]
	s_cbranch_vccz .LBB0_1500
	s_barrier
